# p3a S3 LT epilogues: register copies of the prefetched beta/gcum quads removed (first reads renamed to the prefetch registers), 32 VALU fewer per k-head iteration on the LT waves
# baseline (speedup 1.0000x reference)
.LBB0_615:
	s_mov_b64 s[4:5], -1
	s_andn2_b64 vcc, exec, s[28:29]
	v_lshlrev_b32_e32 v19, 4, v160
	s_waitcnt lgkmcnt(0)
	s_barrier
	s_cbranch_vccnz .LBB0_641
	v_and_b32_e32 v102, 31, v160
	v_ashrrev_i32_e32 v2, 3, v160
	v_and_b32_e32 v20, 0xfffffe0, v160
	v_and_b32_e32 v21, -4, v2
	v_bitop3_b32 v2, v2, v102, -4 bitop3:0x6c
	v_add_lshl_u32 v6, v2, v20, 4
	v_readlane_b32 s4, v248, 11
	v_readlane_b32 s5, v248, 13
	v_add_u32_e32 v98, 8, v21
	v_add_u32_e32 v103, s4, v6
	v_add_u32_e32 v108, s5, v19
	v_readlane_b32 s5, v248, 12
	v_add_u32_e32 v7, 0x4000, v108
	v_bitop3_b32 v98, v98, v160, 31 bitop3:0x78
	v_add_u32_e32 v109, s5, v6
	v_add_lshl_u32 v20, v98, v20, 4
	v_add_u32_e32 v110, s4, v20
	v_add_u32_e32 v20, s5, v20
	v_cndmask_b32_e64 v104, v109, v7, s[20:21]
	v_cndmask_b32_e64 v105, v20, v7, s[20:21]
	ds_read_b128 v[2:5], v103
	ds_read_b128 v[6:9], v104
	ds_read_b128 v[112:115], v110 offset:1024
	ds_read_b128 v[116:119], v105 offset:1024
	ds_read_b128 v[120:123], v103 offset:2048
	ds_read_b128 v[124:127], v104 offset:2048
	ds_read_b128 v[128:131], v110 offset:3072
	ds_read_b128 v[132:135], v105 offset:3072
	ds_read_b128 v[136:139], v103 offset:4096
	ds_read_b128 v[140:143], v104 offset:4096
	ds_read_b128 v[144:147], v110 offset:5120
	ds_read_b128 v[148:151], v105 offset:5120
	ds_read_b128 v[152:155], v103 offset:6144
	ds_read_b128 v[232:235], v104 offset:6144
	ds_read_b128 v[228:231], v110 offset:7168
	ds_read_b128 v[236:239], v105 offset:7168
	v_readlane_b32 s5, v249, 60
	s_movk_i32 s4, 0xc0
	s_mov_b64 s[8:9], -1
	s_waitcnt lgkmcnt(14)
	v_mfma_f32_32x32x16_bf16 v[2:17], v[2:5], v[6:9], 0
	s_lshl_b32 s40, s5, 2
	s_waitcnt lgkmcnt(12)
	v_mfma_f32_32x32x16_bf16 v[2:17], v[112:115], v[116:119], v[2:17]
	s_waitcnt lgkmcnt(10)
	v_mfma_f32_32x32x16_bf16 v[2:17], v[120:123], v[124:127], v[2:17]
	s_waitcnt lgkmcnt(8)
	v_mfma_f32_32x32x16_bf16 v[2:17], v[128:131], v[132:135], v[2:17]
	s_waitcnt lgkmcnt(6)
	v_mfma_f32_32x32x16_bf16 v[2:17], v[136:139], v[140:143], v[2:17]
	s_waitcnt lgkmcnt(4)
	v_mfma_f32_32x32x16_bf16 v[2:17], v[144:147], v[148:151], v[2:17]
	s_waitcnt lgkmcnt(2)
	v_mfma_f32_32x32x16_bf16 v[2:17], v[152:155], v[232:235], v[2:17]
	s_waitcnt lgkmcnt(0)
	v_mfma_f32_32x32x16_bf16 v[2:17], v[228:231], v[236:239], v[2:17]
	v_or_b32_e32 v100, s5, v102
	v_add_u32_e32 v20, 1, v100
	v_lshrrev_b32_e32 v98, 2, v20
	v_and_b32_e32 v103, 0x7c, v20
	v_add_u32_e32 v99, -1, v98
	v_mul_i32_i24_e32 v98, -8, v98
	v_lshlrev_b32_e32 v101, 8, v99
	v_mul_lo_u32 v98, v98, v99
	v_and_b32_e32 v20, 3, v20
	v_sub_u32_e32 v99, 64, v103
	v_mad_u32_u24 v20, v99, v20, v101
	v_add3_u32 v20, v20, v98, s4
	v_readlane_b32 s4, v249, 61
	v_cmp_gt_u32_e64 s[6:7], 3, v100
	v_lshlrev_b32_e32 v98, 6, v102
	v_add_u32_e32 v101, s4, v21
	s_lshl_b32 s4, s64, 9
	s_add_i32 s46, s4, 0
	s_add_i32 s46, s46, 0x21000
	s_add_i32 s4, s46, s40
	v_lshl_add_u32 v21, v102, 2, s4
	ds_read_b32 v117, v21
	v_readlane_b32 s4, v249, 58
	v_sub_u32_e32 v99, 0, v103
	v_readlane_b32 s5, v249, 59
	s_and_b64 vcc, exec, s[4:5]
	v_lshlrev_b32_e32 v114, 2, v99
	v_cmp_ge_i32_e64 s[4:5], v101, v103
	v_cndmask_b32_e64 v116, v20, v98, s[6:7]
	s_cbranch_vccz .LBB0_626
	s_lshl_b32 s6, s64, 7
	s_mul_i32 s7, s64, 0x4200
	s_add_i32 s7, s7, 0
	s_lshl_b32 s6, s6, 2
	s_add_i32 s7, s7, 0x10000
	v_lshlrev_b32_e32 v20, 2, v116
	s_add_i32 s8, s6, 0
	v_add3_u32 v20, s7, v20, v114
	s_add_i32 s8, s8, 0x20800
	v_lshlrev_b32_e32 v152, 2, v101
	v_add_u32_e32 v153, s8, v152
	v_add_u32_e32 v152, s46, v152
	ds_read_b128 v[120:123], v153
	ds_read_b128 v[124:127], v152
	ds_read_b128 v[128:131], v153 offset:32
	ds_read_b128 v[132:135], v152 offset:32
	ds_read_b128 v[136:139], v153 offset:64
	ds_read_b128 v[140:143], v152 offset:64
	ds_read_b128 v[144:147], v153 offset:96
	ds_read_b128 v[148:151], v152 offset:96
	s_and_saveexec_b64 s[6:7], s[4:5]
	s_cbranch_execz .LBB0_619
	v_lshlrev_b32_e32 v21, 2, v101
	v_add_u32_e32 v98, s8, v21
	v_add_u32_e32 v99, s46, v21
	s_waitcnt lgkmcnt(6)
	v_cmp_gt_i32_e32 vcc, v101, v100
	v_add_u32_e32 v21, v20, v21
	v_mul_f32_e32 v98, v2, v120
	v_sub_f32_e32 v99, v124, v117
	v_mul_f32_e32 v99, 0x3fb8aa3b, v99
	v_exp_f32_e32 v99, v99
	v_sub_f32_e32 v104, v125, v117
	v_mul_f32_e32 v104, 0x3fb8aa3b, v104
	v_exp_f32_e32 v108, v104
	v_mul_f32_e32 v98, v98, v99
	v_cndmask_b32_e32 v104, 0, v98, vcc
	v_mul_f32_e32 v98, v3, v121
	v_mul_f32_e32 v98, v98, v108
	v_cmp_ge_i32_e32 vcc, v101, v100
	v_sub_f32_e32 v99, v127, v117
	v_mul_f32_e32 v99, 0x3fb8aa3b, v99
	v_cndmask_b32_e32 v105, 0, v98, vcc
	v_sub_f32_e32 v98, v126, v117
	v_mul_f32_e32 v98, 0x3fb8aa3b, v98
	v_exp_f32_e32 v98, v98
	v_exp_f32_e32 v99, v99
	v_or_b32_e32 v108, 3, v101
	v_pk_mul_f32 v[106:107], v[4:5], v[122:123]
	v_or_b32_e32 v109, 2, v101
	v_pk_mul_f32 v[98:99], v[106:107], v[98:99]
	v_cmp_gt_i32_e32 vcc, v108, v100
	s_nop 1
	v_cndmask_b32_e32 v107, 0, v99, vcc
	v_cmp_gt_i32_e32 vcc, v109, v100
	s_nop 1
	v_cndmask_b32_e32 v106, 0, v98, vcc
	ds_write_b128 v21, v[104:107]
.LBB0_619:
	s_or_b64 exec, exec, s[6:7]
	v_add_u32_e32 v21, 8, v101
	v_cmp_ge_i32_e32 vcc, v21, v103
	s_and_saveexec_b64 s[4:5], vcc
	s_cbranch_execz .LBB0_621
	v_lshlrev_b32_e32 v112, 2, v101
	v_add_u32_e32 v98, s8, v112
	v_add_u32_e32 v99, s46, v112
	s_waitcnt lgkmcnt(4)
	v_cmp_gt_i32_e32 vcc, v21, v100
	v_mul_f32_e32 v98, v6, v128
	v_sub_f32_e32 v99, v132, v117
	v_mul_f32_e32 v99, 0x3fb8aa3b, v99
	v_exp_f32_e32 v99, v99
	v_sub_f32_e32 v104, v133, v117
	v_mul_f32_e32 v104, 0x3fb8aa3b, v104
	v_exp_f32_e32 v108, v104
	v_mul_f32_e32 v98, v98, v99
	v_cndmask_b32_e32 v104, 0, v98, vcc
	v_mul_f32_e32 v98, v7, v129
	v_mul_f32_e32 v98, v98, v108
	v_cmp_ge_i32_e32 vcc, v21, v100
	v_sub_f32_e32 v99, v135, v117
	v_mul_f32_e32 v99, 0x3fb8aa3b, v99
	v_cndmask_b32_e32 v105, 0, v98, vcc
	v_sub_f32_e32 v98, v134, v117
	v_mul_f32_e32 v98, 0x3fb8aa3b, v98
	v_exp_f32_e32 v98, v98
	v_exp_f32_e32 v99, v99
	v_or_b32_e32 v108, 3, v21
	v_pk_mul_f32 v[106:107], v[8:9], v[130:131]
	v_or_b32_e32 v21, 2, v21
	v_pk_mul_f32 v[98:99], v[106:107], v[98:99]
	v_cmp_gt_i32_e32 vcc, v108, v100
	s_nop 1
	v_cndmask_b32_e32 v107, 0, v99, vcc
	v_cmp_gt_i32_e32 vcc, v21, v100
	v_add_u32_e32 v21, v20, v112
	s_nop 0
	v_cndmask_b32_e32 v106, 0, v98, vcc
	ds_write_b128 v21, v[104:107] offset:32
.LBB0_621:
	s_or_b64 exec, exec, s[4:5]
	v_add_u32_e32 v21, 16, v101
	v_cmp_ge_i32_e32 vcc, v21, v103
	s_and_saveexec_b64 s[4:5], vcc
	s_cbranch_execz .LBB0_623
	v_lshlrev_b32_e32 v112, 2, v101
	v_add_u32_e32 v98, s8, v112
	v_add_u32_e32 v99, s46, v112
	s_waitcnt lgkmcnt(2)
	v_cmp_gt_i32_e32 vcc, v21, v100
	v_mul_f32_e32 v98, v10, v136
	v_sub_f32_e32 v99, v140, v117
	v_mul_f32_e32 v99, 0x3fb8aa3b, v99
	v_exp_f32_e32 v99, v99
	v_sub_f32_e32 v104, v141, v117
	v_mul_f32_e32 v104, 0x3fb8aa3b, v104
	v_exp_f32_e32 v108, v104
	v_mul_f32_e32 v98, v98, v99
	v_cndmask_b32_e32 v104, 0, v98, vcc
	v_mul_f32_e32 v98, v11, v137
	v_mul_f32_e32 v98, v98, v108
	v_cmp_ge_i32_e32 vcc, v21, v100
	v_sub_f32_e32 v99, v143, v117
	v_mul_f32_e32 v99, 0x3fb8aa3b, v99
	v_cndmask_b32_e32 v105, 0, v98, vcc
	v_sub_f32_e32 v98, v142, v117
	v_mul_f32_e32 v98, 0x3fb8aa3b, v98
	v_exp_f32_e32 v98, v98
	v_exp_f32_e32 v99, v99
	v_or_b32_e32 v108, 3, v21
	v_pk_mul_f32 v[106:107], v[12:13], v[138:139]
	v_or_b32_e32 v21, 2, v21
	v_pk_mul_f32 v[98:99], v[106:107], v[98:99]
	v_cmp_gt_i32_e32 vcc, v108, v100
	s_nop 1
	v_cndmask_b32_e32 v107, 0, v99, vcc
	v_cmp_gt_i32_e32 vcc, v21, v100
	v_add_u32_e32 v21, v20, v112
	s_nop 0
	v_cndmask_b32_e32 v106, 0, v98, vcc
	ds_write_b128 v21, v[104:107] offset:64
.LBB0_623:
	s_or_b64 exec, exec, s[4:5]
	v_add_u32_e32 v21, 24, v101
	v_cmp_ge_i32_e32 vcc, v21, v103
	s_and_saveexec_b64 s[4:5], vcc
	s_cbranch_execz .LBB0_625
	v_lshlrev_b32_e32 v112, 2, v101
	v_add_u32_e32 v98, s8, v112
	v_add_u32_e32 v99, s46, v112
	s_waitcnt lgkmcnt(0)
	v_cmp_gt_i32_e32 vcc, v21, v100
	v_add_u32_e32 v20, v20, v112
	v_mul_f32_e32 v98, v14, v144
	v_sub_f32_e32 v99, v148, v117
	v_mul_f32_e32 v99, 0x3fb8aa3b, v99
	v_exp_f32_e32 v99, v99
	v_sub_f32_e32 v104, v149, v117
	v_mul_f32_e32 v104, 0x3fb8aa3b, v104
	v_exp_f32_e32 v108, v104
	v_mul_f32_e32 v98, v98, v99
	v_cndmask_b32_e32 v104, 0, v98, vcc
	v_mul_f32_e32 v98, v15, v145
	v_mul_f32_e32 v98, v98, v108
	v_cmp_ge_i32_e32 vcc, v21, v100
	v_sub_f32_e32 v99, v151, v117
	v_mul_f32_e32 v99, 0x3fb8aa3b, v99
	v_cndmask_b32_e32 v105, 0, v98, vcc
	v_sub_f32_e32 v98, v150, v117
	v_mul_f32_e32 v98, 0x3fb8aa3b, v98
	v_exp_f32_e32 v98, v98
	v_exp_f32_e32 v99, v99
	v_or_b32_e32 v108, 3, v21
	v_pk_mul_f32 v[106:107], v[16:17], v[146:147]
	v_or_b32_e32 v21, 2, v21
	v_pk_mul_f32 v[98:99], v[106:107], v[98:99]
	v_cmp_gt_i32_e32 vcc, v108, v100
	s_nop 1
	v_cndmask_b32_e32 v107, 0, v99, vcc
	v_cmp_gt_i32_e32 vcc, v21, v100
	s_nop 1
	v_cndmask_b32_e32 v106, 0, v98, vcc
	ds_write_b128 v20, v[104:107] offset:96

.LBB0_628:
	s_lshl_b32 s4, s64, 1
	s_or_b32 s7, s4, 1
	s_lshl_b32 s4, s7, 8
	s_add_i32 s6, s4, 0
	s_add_i32 s6, s6, 0x21000
	s_add_i32 s4, s6, s40
	v_lshl_add_u32 v102, v102, 2, s4
	ds_read_b32 v102, v102
	v_readlane_b32 s4, v249, 58
	v_readlane_b32 s5, v249, 59
	s_andn2_b64 vcc, exec, s[4:5]
	s_mov_b64 s[4:5], -1
	s_mov_b32 s16, s47
	s_mov_b32 s17, 0x24300000
	s_cbranch_vccnz .LBB0_638
	s_lshl_b32 s4, s7, 6
	s_mulk_i32 s7, 0x2100
	s_add_i32 s5, s7, 0
	s_lshl_b32 s4, s4, 2
	s_add_i32 s5, s5, 0x10000
	v_lshlrev_b32_e32 v116, 2, v116
	s_add_i32 s4, s4, 0
	v_add3_u32 v114, s5, v116, v114
	s_add_i32 s4, s4, 0x20800
	v_lshlrev_b32_e32 v118, 2, v101
	v_cmp_ge_i32_e32 vcc, v101, v103
	s_waitcnt lgkmcnt(1)
	v_add_u32_e32 v117, s4, v118
	v_add_u32_e32 v116, s6, v118
	v_add_u32_e32 v114, v114, v118
	ds_read_b128 v[126:129], v117
	ds_read_b128 v[130:133], v116
	ds_read_b128 v[134:137], v117 offset:32
	ds_read_b128 v[138:141], v116 offset:32
	ds_read_b128 v[142:145], v117 offset:64
	ds_read_b128 v[146:149], v116 offset:64
	ds_read_b128 v[150:153], v117 offset:96
	ds_read_b128 v[154:157], v116 offset:96
	s_and_saveexec_b64 s[4:5], vcc
	s_cbranch_execz .LBB0_633
	s_waitcnt lgkmcnt(6)
	v_cmp_gt_i32_e32 vcc, v101, v100
	v_mul_f32_e32 v118, v2, v126
	v_sub_f32_e32 v122, v130, v102
	v_sub_f32_e32 v123, v131, v102
	v_mul_f32_e32 v122, 0x3fb8aa3b, v122
	v_mul_f32_e32 v123, 0x3fb8aa3b, v123
	v_exp_f32_e32 v122, v122
	v_exp_f32_e32 v123, v123
	v_mul_f32_e32 v119, v3, v127
	v_pk_mul_f32 v[120:121], v[4:5], v[128:129]
	v_mul_f32_e32 v118, v118, v122
	v_mul_f32_e32 v119, v119, v123
	v_sub_f32_e32 v122, v132, v102
	v_sub_f32_e32 v123, v133, v102
	v_mul_f32_e32 v122, 0x3fb8aa3b, v122
	v_mul_f32_e32 v123, 0x3fb8aa3b, v123
	v_exp_f32_e32 v122, v122
	v_exp_f32_e32 v123, v123
	v_cndmask_b32_e32 v118, 0, v118, vcc
	v_cmp_ge_i32_e32 vcc, v101, v100
	v_pk_mul_f32 v[120:121], v[120:121], v[122:123]
	s_nop 0
	v_cndmask_b32_e32 v119, 0, v119, vcc
	v_cmp_gt_i32_e32 vcc, v115, v100
	s_nop 1
	v_cndmask_b32_e32 v121, 0, v121, vcc
	v_cmp_gt_i32_e32 vcc, v113, v100
	s_nop 1
	v_cndmask_b32_e32 v120, 0, v120, vcc
	ds_write_b128 v114, v[118:121]
	s_or_b64 exec, exec, s[4:5]
	v_cmp_ge_i32_e32 vcc, v112, v103
	s_and_saveexec_b64 s[4:5], vcc
	s_cbranch_execnz .LBB0_634

.LBB0_632:
	s_waitcnt lgkmcnt(2)
	v_cmp_gt_i32_e32 vcc, v107, v100
	v_mul_f32_e32 v118, v10, v142
	v_sub_f32_e32 v122, v146, v102
	v_sub_f32_e32 v123, v147, v102
	v_mul_f32_e32 v122, 0x3fb8aa3b, v122
	v_mul_f32_e32 v123, 0x3fb8aa3b, v123
	v_exp_f32_e32 v122, v122
	v_exp_f32_e32 v123, v123
	v_mul_f32_e32 v119, v11, v143
	v_pk_mul_f32 v[120:121], v[12:13], v[144:145]
	v_mul_f32_e32 v118, v118, v122
	v_mul_f32_e32 v119, v119, v123
	v_sub_f32_e32 v122, v148, v102
	v_sub_f32_e32 v123, v149, v102
	v_mul_f32_e32 v122, 0x3fb8aa3b, v122
	v_mul_f32_e32 v123, 0x3fb8aa3b, v123
	v_exp_f32_e32 v122, v122
	v_exp_f32_e32 v123, v123
	v_cndmask_b32_e32 v118, 0, v118, vcc
	v_cmp_ge_i32_e32 vcc, v107, v100
	v_pk_mul_f32 v[120:121], v[120:121], v[122:123]
	s_nop 0
	v_cndmask_b32_e32 v119, 0, v119, vcc
	v_cmp_gt_i32_e32 vcc, v109, v100
	s_nop 1
	v_cndmask_b32_e32 v121, 0, v121, vcc
	v_cmp_gt_i32_e32 vcc, v108, v100
	s_nop 1
	v_cndmask_b32_e32 v120, 0, v120, vcc
	ds_write_b128 v114, v[118:121] offset:64
	s_or_b64 exec, exec, s[4:5]
	v_cmp_ge_i32_e32 vcc, v104, v103
	s_and_saveexec_b64 s[4:5], vcc
	s_cbranch_execnz .LBB0_636
	s_branch .LBB0_637

.LBB0_634:
	s_waitcnt lgkmcnt(4)
	v_cmp_gt_i32_e32 vcc, v112, v100
	v_mul_f32_e32 v118, v6, v134
	v_sub_f32_e32 v122, v138, v102
	v_sub_f32_e32 v123, v139, v102
	v_mul_f32_e32 v122, 0x3fb8aa3b, v122
	v_mul_f32_e32 v123, 0x3fb8aa3b, v123
	v_exp_f32_e32 v122, v122
	v_exp_f32_e32 v123, v123
	v_mul_f32_e32 v119, v7, v135
	v_pk_mul_f32 v[120:121], v[8:9], v[136:137]
	v_mul_f32_e32 v118, v118, v122
	v_mul_f32_e32 v119, v119, v123
	v_sub_f32_e32 v122, v140, v102
	v_sub_f32_e32 v123, v141, v102
	v_mul_f32_e32 v122, 0x3fb8aa3b, v122
	v_mul_f32_e32 v123, 0x3fb8aa3b, v123
	v_exp_f32_e32 v122, v122
	v_exp_f32_e32 v123, v123
	v_cndmask_b32_e32 v118, 0, v118, vcc
	v_cmp_ge_i32_e32 vcc, v112, v100
	v_pk_mul_f32 v[120:121], v[120:121], v[122:123]
	s_nop 0
	v_cndmask_b32_e32 v119, 0, v119, vcc
	v_cmp_gt_i32_e32 vcc, v111, v100
	s_nop 1
	v_cndmask_b32_e32 v121, 0, v121, vcc
	v_cmp_gt_i32_e32 vcc, v110, v100
	s_nop 1
	v_cndmask_b32_e32 v120, 0, v120, vcc
	ds_write_b128 v114, v[118:121] offset:32
	s_or_b64 exec, exec, s[4:5]
	v_cmp_ge_i32_e32 vcc, v107, v103
	s_and_saveexec_b64 s[4:5], vcc
	s_cbranch_execnz .LBB0_632

.LBB0_636:
	s_waitcnt lgkmcnt(0)
	v_cmp_gt_i32_e32 vcc, v104, v100
	v_mul_f32_e32 v103, v14, v150
	v_sub_f32_e32 v116, v154, v102
	v_mul_f32_e32 v116, 0x3fb8aa3b, v116
	v_sub_f32_e32 v118, v155, v102
	v_exp_f32_e32 v116, v116
	v_mul_f32_e32 v118, 0x3fb8aa3b, v118
	v_exp_f32_e32 v118, v118
	v_mul_f32_e32 v117, v15, v151
	v_mul_f32_e32 v103, v103, v116
	v_cndmask_b32_e32 v116, 0, v103, vcc
	v_mul_f32_e32 v103, v117, v118
	v_sub_f32_e32 v117, v156, v102
	v_mul_f32_e32 v117, 0x3fb8aa3b, v117
	v_exp_f32_e32 v118, v117
	v_sub_f32_e32 v117, v157, v102
	v_mul_f32_e32 v117, 0x3fb8aa3b, v117
	v_exp_f32_e32 v119, v117
	v_cmp_ge_i32_e32 vcc, v104, v100
	v_pk_mul_f32 v[120:121], v[16:17], v[152:153]
	s_nop 0
	v_cndmask_b32_e32 v117, 0, v103, vcc
	v_pk_mul_f32 v[118:119], v[120:121], v[118:119]
	v_cmp_gt_i32_e32 vcc, v106, v100
	s_nop 1
	v_cndmask_b32_e32 v119, 0, v119, vcc
	v_cmp_gt_i32_e32 vcc, v105, v100
	s_nop 1
	v_cndmask_b32_e32 v118, 0, v118, vcc
	ds_write_b128 v114, v[116:119] offset:96
